# v15 + attention QK: second half of the K-fragment LDS reads issued with the first batch / behind the consuming MFMA (one LDS round trip per tile instead of two)
# baseline (speedup 1.0000x reference)
.LBB0_1551:
	s_and_b32 s4, s6, 1
	s_mul_i32 s5, s4, 0x4400
	v_add_u32_e32 v193, s5, v211
	ds_read_b128 v[172:175], v193 offset:224
	ds_read_b128 v[68:71], v193 offset:192
	ds_read_b128 v[72:75], v193 offset:160
	ds_read_b128 v[76:79], v193 offset:128
	ds_read_b128 v[160:163], v193 offset:96
	ds_read_b128 v[164:167], v193 offset:64
	ds_read_b128 v[80:83], v193
	ds_read_b128 v[168:171], v193 offset:32
	ds_read_b128 v[64:67], v193 offset:8704
	ds_read_b128 v[224:227], v193 offset:8736
	ds_read_b128 v[218:221], v193 offset:8768
	ds_read_b128 v[202:205], v193 offset:8800
	v_lshrrev_b64 v[196:197], v178, v[196:197]
	s_waitcnt lgkmcnt(4)
	s_nop 0
	v_mfma_f32_32x32x16_bf16 v[80:95], v[80:83], v[120:123], 0
	v_mfma_f32_32x32x16_bf16 v[80:95], v[168:171], v[96:99], v[80:95]
	ds_read_b128 v[168:171], v193 offset:8864
	v_mfma_f32_32x32x16_bf16 v[80:95], v[164:167], v[100:103], v[80:95]
	ds_read_b128 v[164:167], v193 offset:8896
	v_mfma_f32_32x32x16_bf16 v[80:95], v[160:163], v[104:107], v[80:95]
	ds_read_b128 v[160:163], v193 offset:8928
	v_mfma_f32_32x32x16_bf16 v[80:95], v[76:79], v[108:111], v[80:95]
	v_mfma_f32_32x32x16_bf16 v[80:95], v[72:75], v[112:115], v[80:95]
	v_mfma_f32_32x32x16_bf16 v[80:95], v[68:71], v[116:119], v[80:95]
	v_mfma_f32_32x32x16_bf16 v[80:95], v[172:175], v[124:127], v[80:95]
	ds_read_b128 v[172:175], v193 offset:8832
	s_waitcnt lgkmcnt(4)
	s_nop 0
	v_mfma_f32_32x32x16_bf16 v[64:79], v[64:67], v[120:123], 0
	v_mfma_f32_32x32x16_bf16 v[64:79], v[224:227], v[96:99], v[64:79]
	v_mfma_f32_32x32x16_bf16 v[64:79], v[218:221], v[100:103], v[64:79]
	v_mfma_f32_32x32x16_bf16 v[64:79], v[202:205], v[104:107], v[64:79]
	v_bfe_i32 v230, v196, 0, 1
	v_bfe_i32 v202, v196, 1, 1
	v_bfi_b32 v80, v230, v80, v241
	v_bfi_b32 v202, v202, v81, v241
	v_bfe_i32 v203, v196, 2, 1
	v_bfe_i32 v204, v196, 3, 1
	v_bfi_b32 v203, v203, v82, v241
	v_bfi_b32 v204, v204, v83, v241
	s_waitcnt lgkmcnt(0)
	v_mfma_f32_32x32x16_bf16 v[64:79], v[172:175], v[108:111], v[64:79]
	v_bfe_i32 v205, v196, 8, 1
	v_bfe_i32 v217, v196, 9, 1
	v_bfi_b32 v205, v205, v84, v241
	v_bfi_b32 v217, v217, v85, v241
	v_bfe_i32 v218, v196, 10, 1
	v_bfe_i32 v219, v196, 11, 1
	v_bfi_b32 v218, v218, v86, v241
	v_bfi_b32 v219, v219, v87, v241
	v_mfma_f32_32x32x16_bf16 v[64:79], v[168:171], v[112:115], v[64:79]
	v_bfe_i32 v220, v196, 16, 1
	v_bfe_i32 v221, v196, 17, 1
	v_bfi_b32 v220, v220, v88, v241
	v_bfi_b32 v221, v221, v89, v241
	v_bfe_i32 v224, v196, 18, 1
	v_bfe_i32 v225, v196, 19, 1
	v_bfi_b32 v224, v224, v90, v241
	v_bfi_b32 v225, v225, v91, v241
	v_mfma_f32_32x32x16_bf16 v[64:79], v[164:167], v[116:119], v[64:79]
	v_bfe_i32 v226, v196, 24, 1
	v_bfe_i32 v227, v196, 25, 1
	v_bfi_b32 v226, v226, v92, v241
	v_bfi_b32 v227, v227, v93, v241
	v_bfe_i32 v228, v196, 26, 1
	v_bfe_i32 v229, v196, 27, 1
	v_bfi_b32 v228, v228, v94, v241
	v_bfi_b32 v229, v229, v95, v241
	v_mfma_f32_32x32x16_bf16 v[64:79], v[160:163], v[124:127], v[64:79]
	v_max3_f32 v81, v80, s80, v202
	v_max3_f32 v81, v81, v203, v204
	v_max3_f32 v81, v81, v205, v217
	v_max3_f32 v81, v81, v218, v219
	v_max3_f32 v81, v81, v220, v221
	v_max3_f32 v81, v81, v224, v225
	v_max3_f32 v81, v81, v226, v227
	v_max3_f32 v81, v81, v228, v229
	v_add_u32_e32 v160, s5, v212
	v_add_u32_e32 v215, 0x8800, v160
	v_add_u32_e32 v214, 0x9800, v160
	v_add_u32_e32 v195, 0xa800, v160
	v_add_u32_e32 v193, 0xb800, v160
	ds_read2_b64 v[172:175], v215 offset1:2
	ds_read2_b64 v[168:171], v214 offset0:32 offset1:34
	ds_read2_b64 v[164:167], v195 offset0:64 offset1:66
	ds_read2_b64 v[160:163], v193 offset0:96 offset1:98
	v_bfe_i32 v83, v197, 0, 1
	v_bfe_i32 v84, v197, 1, 1
	v_bfi_b32 v64, v83, v64, v241
	v_bfi_b32 v65, v84, v65, v241
	v_max3_f32 v81, v81, v64, v65
	v_bfe_i32 v83, v197, 2, 1
	v_bfe_i32 v84, v197, 3, 1
	v_bfi_b32 v66, v83, v66, v241
	v_bfi_b32 v67, v84, v67, v241
	v_max3_f32 v81, v81, v66, v67
	v_bfe_i32 v83, v197, 8, 1
	v_bfe_i32 v84, v197, 9, 1
	v_bfi_b32 v68, v83, v68, v241
	v_bfi_b32 v69, v84, v69, v241
	v_max3_f32 v81, v81, v68, v69
	v_bfe_i32 v83, v197, 10, 1
	v_bfe_i32 v84, v197, 11, 1
	v_bfi_b32 v70, v83, v70, v241
	v_bfi_b32 v71, v84, v71, v241
	v_max3_f32 v81, v81, v70, v71
	v_bfe_i32 v83, v197, 16, 1
	v_bfe_i32 v84, v197, 17, 1
	v_bfi_b32 v72, v83, v72, v241
	v_bfi_b32 v73, v84, v73, v241
	v_max3_f32 v81, v81, v72, v73
	v_bfe_i32 v83, v197, 18, 1
	v_bfe_i32 v84, v197, 19, 1
	v_bfi_b32 v74, v83, v74, v241
	v_bfi_b32 v75, v84, v75, v241
	v_max3_f32 v81, v81, v74, v75
	v_bfe_i32 v83, v197, 24, 1
	v_bfe_i32 v84, v197, 25, 1
	v_bfi_b32 v76, v83, v76, v241
	v_bfi_b32 v77, v84, v77, v241
	v_max3_f32 v81, v81, v76, v77
	v_bfe_i32 v83, v197, 26, 1
	v_bfe_i32 v84, v197, 27, 1
	v_bfi_b32 v78, v83, v78, v241
	v_bfi_b32 v79, v84, v79, v241
	v_max3_f32 v81, v81, v78, v79
	v_mbcnt_lo_u32_b32 v82, -1, 0
	v_mbcnt_hi_u32_b32 v82, -1, v82
	s_nop 0
	v_lshlrev_b32_e32 v82, 2, v82
	v_xor_b32_e32 v82, 0x80, v82
	ds_bpermute_b32 v82, v82, v81
	s_waitcnt lgkmcnt(0)
	v_max3_f32 v81, v216, v81, v82
	v_add_f32_e32 v82, 0x41000000, v216
	v_cmp_gt_f32_e32 vcc, v81, v82
	s_nop 1
	s_cbranch_vccnz .Latt_newref
	v_mov_b32_e32 v81, v216
